# v42 + next-bank V fragment reads issued two per PV MFMA instead of 8-read bursts
# baseline (speedup 1.0000x reference)
.LBB0_1185:
	ds_read_b64_tr_b16 v[0:1], v166 offset:32768
	ds_read_b64_tr_b16 v[2:3], v158 offset:32768
	ds_read_b64_tr_b16 v[4:5], v167 offset:32768
	ds_read_b64_tr_b16 v[6:7], v160 offset:32768
	ds_read_b64_tr_b16 v[10:11], v168 offset:32768
	ds_read_b64_tr_b16 v[12:13], v162 offset:32768
	ds_read_b64_tr_b16 v[174:175], v169 offset:32768
	ds_read_b64_tr_b16 v[176:177], v163 offset:32768
	v_exp_f32_e32 v96, v96
	v_exp_f32_e32 v80, v80
	v_exp_f32_e32 v97, v97
	v_exp_f32_e32 v81, v81
	v_add_f32_e32 v9, 0, v96
	v_exp_f32_e32 v98, v98
	v_add_f32_e32 v9, v80, v9
	v_exp_f32_e32 v82, v82
	v_add_f32_e32 v9, v97, v9
	v_exp_f32_e32 v99, v99
	v_add_f32_e32 v9, v81, v9
	v_exp_f32_e32 v83, v83
	v_add_f32_e32 v9, v98, v9
	v_exp_f32_e32 v100, v100
	v_add_f32_e32 v9, v82, v9
	v_exp_f32_e32 v84, v84
	v_add_f32_e32 v9, v99, v9
	v_exp_f32_e32 v101, v101
	v_add_f32_e32 v9, v83, v9
	v_exp_f32_e32 v85, v85
	v_add_f32_e32 v9, v100, v9
	v_exp_f32_e32 v102, v102
	v_add_f32_e32 v9, v84, v9
	v_exp_f32_e32 v86, v86
	v_add_f32_e32 v9, v101, v9
	v_exp_f32_e32 v103, v103
	v_add_f32_e32 v9, v85, v9
	v_exp_f32_e32 v87, v87
	v_add_f32_e32 v9, v102, v9
	v_exp_f32_e32 v104, v104
	v_add_f32_e32 v9, v86, v9
	v_exp_f32_e32 v88, v88
	v_add_f32_e32 v9, v103, v9
	v_exp_f32_e32 v105, v105
	v_add_f32_e32 v9, v87, v9
	v_exp_f32_e32 v89, v89
	v_add_f32_e32 v9, v104, v9
	v_exp_f32_e32 v106, v106
	v_add_f32_e32 v9, v88, v9
	v_exp_f32_e32 v90, v90
	v_add_f32_e32 v9, v105, v9
	v_exp_f32_e32 v107, v107
	v_add_f32_e32 v9, v89, v9
	v_exp_f32_e32 v91, v91
	v_add_f32_e32 v9, v106, v9
	v_exp_f32_e32 v108, v108
	v_add_f32_e32 v9, v90, v9
	v_exp_f32_e32 v92, v92
	v_add_f32_e32 v9, v107, v9
	v_exp_f32_e32 v109, v109
	v_add_f32_e32 v9, v91, v9
	v_exp_f32_e32 v93, v93
	v_add_f32_e32 v9, v108, v9
	v_exp_f32_e32 v110, v110
	v_add_f32_e32 v9, v92, v9
	v_exp_f32_e32 v94, v94
	v_add_f32_e32 v9, v109, v9
	v_exp_f32_e32 v111, v111
	v_add_f32_e32 v9, v93, v9
	v_exp_f32_e32 v95, v95
	v_add_f32_e32 v9, v110, v9
	v_add_f32_e32 v9, v94, v9
	v_add_f32_e32 v9, v111, v9
	v_add_f32_e32 v9, v95, v9
	ds_read_b64_tr_b16 v[178:179], v166 offset:36864
	ds_read_b64_tr_b16 v[180:181], v158 offset:36864
	ds_read_b64_tr_b16 v[182:183], v167 offset:36864
	ds_read_b64_tr_b16 v[184:185], v160 offset:36864
	ds_read_b64_tr_b16 v[186:187], v168 offset:36864
	ds_read_b64_tr_b16 v[188:189], v162 offset:36864
	ds_read_b64_tr_b16 v[190:191], v169 offset:36864
	ds_read_b64_tr_b16 v[192:193], v163 offset:36864
	v_cvt_pk_bf16_f32 v194, v96, v97
	v_cvt_pk_bf16_f32 v195, v98, v99
	v_cvt_pk_bf16_f32 v196, v100, v101
	v_cvt_pk_bf16_f32 v197, v102, v103
	s_waitcnt lgkmcnt(14)
	s_nop 0
	v_mfma_f32_32x32x16_bf16 v[48:63], v[0:3], v[194:197], v[48:63]
	ds_read_b64_tr_b16 v[0:1], v166 offset:40960
	ds_read_b64_tr_b16 v[2:3], v158 offset:40960
	s_waitcnt lgkmcnt(14)
	v_mfma_f32_32x32x16_bf16 v[64:79], v[4:7], v[194:197], v[64:79]
	ds_read_b64_tr_b16 v[4:5], v167 offset:40960
	ds_read_b64_tr_b16 v[6:7], v160 offset:40960
	s_waitcnt lgkmcnt(14)
	v_mfma_f32_32x32x16_bf16 v[32:47], v[10:13], v[194:197], v[32:47]
	ds_read_b64_tr_b16 v[10:11], v168 offset:40960
	ds_read_b64_tr_b16 v[12:13], v162 offset:40960
	s_waitcnt lgkmcnt(14)
	v_mfma_f32_32x32x16_bf16 v[16:31], v[174:177], v[194:197], v[16:31]
	ds_read_b64_tr_b16 v[174:175], v169 offset:40960
	ds_read_b64_tr_b16 v[176:177], v163 offset:40960
	v_cvt_pk_bf16_f32 v194, v104, v105
	v_cvt_pk_bf16_f32 v195, v106, v107
	v_cvt_pk_bf16_f32 v196, v108, v109
	v_cvt_pk_bf16_f32 v197, v110, v111
	s_waitcnt lgkmcnt(14)
	s_nop 0
	v_mfma_f32_32x32x16_bf16 v[48:63], v[178:181], v[194:197], v[48:63]
	ds_read_b64_tr_b16 v[178:179], v166 offset:45056
	ds_read_b64_tr_b16 v[180:181], v158 offset:45056
	s_waitcnt lgkmcnt(14)
	v_mfma_f32_32x32x16_bf16 v[64:79], v[182:185], v[194:197], v[64:79]
	ds_read_b64_tr_b16 v[182:183], v167 offset:45056
	ds_read_b64_tr_b16 v[184:185], v160 offset:45056
	s_waitcnt lgkmcnt(14)
	v_mfma_f32_32x32x16_bf16 v[32:47], v[186:189], v[194:197], v[32:47]
	ds_read_b64_tr_b16 v[186:187], v168 offset:45056
	ds_read_b64_tr_b16 v[188:189], v162 offset:45056
	s_waitcnt lgkmcnt(14)
	v_mfma_f32_32x32x16_bf16 v[16:31], v[190:193], v[194:197], v[16:31]
	ds_read_b64_tr_b16 v[190:191], v169 offset:45056
	ds_read_b64_tr_b16 v[192:193], v163 offset:45056
	v_cvt_pk_bf16_f32 v194, v80, v81
	v_cvt_pk_bf16_f32 v195, v82, v83
	v_cvt_pk_bf16_f32 v196, v84, v85
	v_cvt_pk_bf16_f32 v197, v86, v87
	s_waitcnt lgkmcnt(14)
	s_nop 0
	v_mfma_f32_32x32x16_bf16 v[48:63], v[0:3], v[194:197], v[48:63]
	s_waitcnt lgkmcnt(12)
	v_mfma_f32_32x32x16_bf16 v[64:79], v[4:7], v[194:197], v[64:79]
	s_waitcnt lgkmcnt(10)
	v_mfma_f32_32x32x16_bf16 v[32:47], v[10:13], v[194:197], v[32:47]
	s_waitcnt lgkmcnt(8)
	v_mfma_f32_32x32x16_bf16 v[16:31], v[174:177], v[194:197], v[16:31]
	v_cvt_pk_bf16_f32 v0, v88, v89
	v_cvt_pk_bf16_f32 v1, v90, v91
	v_cvt_pk_bf16_f32 v2, v92, v93
	v_cvt_pk_bf16_f32 v3, v94, v95
	s_waitcnt vmcnt(0) lgkmcnt(0)
	s_barrier
	v_add_f32_e32 v161, v161, v9
	s_waitcnt lgkmcnt(6)
	v_mfma_f32_32x32x16_bf16 v[48:63], v[178:181], v[0:3], v[48:63]
	s_and_b64 vcc, exec, s[42:43]
	s_waitcnt lgkmcnt(4)
	v_mfma_f32_32x32x16_bf16 v[64:79], v[182:185], v[0:3], v[64:79]
	s_waitcnt lgkmcnt(2)
	v_mfma_f32_32x32x16_bf16 v[32:47], v[186:189], v[0:3], v[32:47]
	s_waitcnt lgkmcnt(0)
	v_mfma_f32_32x32x16_bf16 v[16:31], v[190:193], v[0:3], v[16:31]
	s_cbranch_vccnz .LBB0_1197
	s_add_i32 s3, s74, 3
	s_cmp_ge_u32 s3, s17
	s_cbranch_scc1 .LBB0_1199
	s_mov_b32 m0, s27
	s_nop 0
	global_load_lds_dwordx4 v150, s[62:63]
	s_add_i32 s3, s27, 0x400
	s_mov_b32 m0, s3
	s_nop 0
	global_load_lds_dwordx4 v144, s[62:63]
	s_andn2_b64 s[42:43], exec, s[68:69]
	s_andn2_b64 vcc, exec, s[68:69]
	s_cbranch_vccz .LBB0_1200

.LBB0_1196:
	ds_read_b64_tr_b16 v[0:1], v166 offset:49152
	ds_read_b64_tr_b16 v[2:3], v158 offset:49152
	ds_read_b64_tr_b16 v[4:5], v167 offset:49152
	ds_read_b64_tr_b16 v[6:7], v160 offset:49152
	ds_read_b64_tr_b16 v[10:11], v168 offset:49152
	ds_read_b64_tr_b16 v[12:13], v162 offset:49152
	ds_read_b64_tr_b16 v[174:175], v169 offset:49152
	ds_read_b64_tr_b16 v[176:177], v163 offset:49152
	v_exp_f32_e32 v128, v128
	v_exp_f32_e32 v112, v112
	v_exp_f32_e32 v129, v129
	v_exp_f32_e32 v113, v113
	v_add_f32_e32 v9, 0, v128
	v_exp_f32_e32 v130, v130
	v_add_f32_e32 v9, v112, v9
	v_exp_f32_e32 v114, v114
	v_add_f32_e32 v9, v129, v9
	v_exp_f32_e32 v131, v131
	v_add_f32_e32 v9, v113, v9
	v_exp_f32_e32 v115, v115
	v_add_f32_e32 v9, v130, v9
	v_exp_f32_e32 v132, v132
	v_add_f32_e32 v9, v114, v9
	v_exp_f32_e32 v116, v116
	v_add_f32_e32 v9, v131, v9
	v_exp_f32_e32 v133, v133
	v_add_f32_e32 v9, v115, v9
	v_exp_f32_e32 v117, v117
	v_add_f32_e32 v9, v132, v9
	v_exp_f32_e32 v134, v134
	v_add_f32_e32 v9, v116, v9
	v_exp_f32_e32 v118, v118
	v_add_f32_e32 v9, v133, v9
	v_exp_f32_e32 v135, v135
	v_add_f32_e32 v9, v117, v9
	v_exp_f32_e32 v119, v119
	v_add_f32_e32 v9, v134, v9
	v_exp_f32_e32 v136, v136
	v_add_f32_e32 v9, v118, v9
	v_exp_f32_e32 v120, v120
	v_add_f32_e32 v9, v135, v9
	v_exp_f32_e32 v137, v137
	v_add_f32_e32 v9, v119, v9
	v_exp_f32_e32 v121, v121
	v_add_f32_e32 v9, v136, v9
	v_exp_f32_e32 v138, v138
	v_add_f32_e32 v9, v120, v9
	v_exp_f32_e32 v122, v122
	v_add_f32_e32 v9, v137, v9
	v_exp_f32_e32 v139, v139
	v_add_f32_e32 v9, v121, v9
	v_exp_f32_e32 v123, v123
	v_add_f32_e32 v9, v138, v9
	v_exp_f32_e32 v140, v140
	v_add_f32_e32 v9, v122, v9
	v_exp_f32_e32 v124, v124
	v_add_f32_e32 v9, v139, v9
	v_exp_f32_e32 v141, v141
	v_add_f32_e32 v9, v123, v9
	v_exp_f32_e32 v125, v125
	v_add_f32_e32 v9, v140, v9
	v_exp_f32_e32 v142, v142
	v_add_f32_e32 v9, v124, v9
	v_exp_f32_e32 v126, v126
	v_add_f32_e32 v9, v141, v9
	v_exp_f32_e32 v143, v143
	v_add_f32_e32 v9, v125, v9
	v_exp_f32_e32 v127, v127
	v_add_f32_e32 v9, v142, v9
	v_add_f32_e32 v9, v126, v9
	v_add_f32_e32 v9, v143, v9
	v_add_f32_e32 v9, v127, v9
	ds_read_b64_tr_b16 v[178:179], v166 offset:53248
	ds_read_b64_tr_b16 v[180:181], v158 offset:53248
	ds_read_b64_tr_b16 v[182:183], v167 offset:53248
	ds_read_b64_tr_b16 v[184:185], v160 offset:53248
	ds_read_b64_tr_b16 v[186:187], v168 offset:53248
	ds_read_b64_tr_b16 v[188:189], v162 offset:53248
	ds_read_b64_tr_b16 v[190:191], v169 offset:53248
	ds_read_b64_tr_b16 v[192:193], v163 offset:53248
	v_cvt_pk_bf16_f32 v194, v128, v129
	v_cvt_pk_bf16_f32 v195, v130, v131
	v_cvt_pk_bf16_f32 v196, v132, v133
	v_cvt_pk_bf16_f32 v197, v134, v135
	s_waitcnt lgkmcnt(14)
	s_nop 0
	v_mfma_f32_32x32x16_bf16 v[48:63], v[0:3], v[194:197], v[48:63]
	ds_read_b64_tr_b16 v[0:1], v166 offset:57344
	ds_read_b64_tr_b16 v[2:3], v158 offset:57344
	s_waitcnt lgkmcnt(14)
	v_mfma_f32_32x32x16_bf16 v[64:79], v[4:7], v[194:197], v[64:79]
	ds_read_b64_tr_b16 v[4:5], v167 offset:57344
	ds_read_b64_tr_b16 v[6:7], v160 offset:57344
	s_waitcnt lgkmcnt(14)
	v_mfma_f32_32x32x16_bf16 v[32:47], v[10:13], v[194:197], v[32:47]
	ds_read_b64_tr_b16 v[10:11], v168 offset:57344
	ds_read_b64_tr_b16 v[12:13], v162 offset:57344
	s_waitcnt lgkmcnt(14)
	v_mfma_f32_32x32x16_bf16 v[16:31], v[174:177], v[194:197], v[16:31]
	ds_read_b64_tr_b16 v[174:175], v169 offset:57344
	ds_read_b64_tr_b16 v[176:177], v163 offset:57344
	v_cvt_pk_bf16_f32 v194, v136, v137
	v_cvt_pk_bf16_f32 v195, v138, v139
	v_cvt_pk_bf16_f32 v196, v140, v141
	v_cvt_pk_bf16_f32 v197, v142, v143
	s_waitcnt lgkmcnt(14)
	s_nop 0
	v_mfma_f32_32x32x16_bf16 v[48:63], v[178:181], v[194:197], v[48:63]
	ds_read_b64_tr_b16 v[178:179], v166 offset:61440
	ds_read_b64_tr_b16 v[180:181], v158 offset:61440
	s_waitcnt lgkmcnt(14)
	v_mfma_f32_32x32x16_bf16 v[64:79], v[182:185], v[194:197], v[64:79]
	ds_read_b64_tr_b16 v[182:183], v167 offset:61440
	ds_read_b64_tr_b16 v[184:185], v160 offset:61440
	s_waitcnt lgkmcnt(14)
	v_mfma_f32_32x32x16_bf16 v[32:47], v[186:189], v[194:197], v[32:47]
	ds_read_b64_tr_b16 v[186:187], v168 offset:61440
	ds_read_b64_tr_b16 v[188:189], v162 offset:61440
	s_waitcnt lgkmcnt(14)
	v_mfma_f32_32x32x16_bf16 v[16:31], v[190:193], v[194:197], v[16:31]
	ds_read_b64_tr_b16 v[170:171], v169 offset:61440
	ds_read_b64_tr_b16 v[172:173], v163 offset:61440
	v_cvt_pk_bf16_f32 v190, v112, v113
	v_cvt_pk_bf16_f32 v191, v114, v115
	v_cvt_pk_bf16_f32 v192, v116, v117
	v_cvt_pk_bf16_f32 v193, v118, v119
	s_waitcnt lgkmcnt(14)
	s_nop 0
	v_mfma_f32_32x32x16_bf16 v[48:63], v[0:3], v[190:193], v[48:63]
	s_waitcnt lgkmcnt(12)
	v_mfma_f32_32x32x16_bf16 v[64:79], v[4:7], v[190:193], v[64:79]
	s_waitcnt lgkmcnt(10)
	v_mfma_f32_32x32x16_bf16 v[32:47], v[10:13], v[190:193], v[32:47]
	s_waitcnt lgkmcnt(8)
	v_mfma_f32_32x32x16_bf16 v[16:31], v[174:177], v[190:193], v[16:31]
	v_cvt_pk_bf16_f32 v0, v120, v121
	v_cvt_pk_bf16_f32 v1, v122, v123
	v_cvt_pk_bf16_f32 v2, v124, v125
	v_cvt_pk_bf16_f32 v3, v126, v127
	s_waitcnt vmcnt(0) lgkmcnt(0)
	s_barrier
	v_add_f32_e32 v161, v161, v9
	s_waitcnt lgkmcnt(6)
	v_mfma_f32_32x32x16_bf16 v[48:63], v[178:181], v[0:3], v[48:63]
	s_waitcnt lgkmcnt(4)
	v_mfma_f32_32x32x16_bf16 v[64:79], v[182:185], v[0:3], v[64:79]
	s_waitcnt lgkmcnt(2)
	v_mfma_f32_32x32x16_bf16 v[32:47], v[186:189], v[0:3], v[32:47]
	s_waitcnt lgkmcnt(0)
	v_mfma_f32_32x32x16_bf16 v[16:31], v[170:173], v[0:3], v[16:31]
